# attention item epilogue: row-sum exchange between the wave halves via v_permlane32_swap instead of two ds_bpermute round trips (instruction selection)
# baseline (speedup 1.0000x reference)
; __device__ __forceinline__ unsigned cvt_pk_bf16(float lo, float hi) { unsigned r; asm("v_cvt_pk_bf16_f32 %0, %1, %2" : "=v"(r) : "v"(lo), "v"(hi)); return r; }
; __device__ __forceinline__ void attn_mfma(PP p, unsigned char* shm, int wv) {
;     ...
; #pragma unroll
;         for (int qi = 0; qi < 2; ++qi) {
;             const float lt = lrun[qi] + __shfl_xor(lrun[qi], 32);
;             const float inv = 1.0f / lt;
;             bf16_t* orow = att + (size_t)(qrow0 + 32 * qi + l31) * 512 + hq * 64;
; #pragma unroll
;             for (int db = 0; db < 2; ++db)
; #pragma unroll
;                 for (int g4 = 0; g4 < 4; ++g4) {
;                     u32x2 w; w.x = cvt_pk_bf16(oacc[db][qi][4 * g4] * inv, oacc[db][qi][4 * g4 + 1] * inv); w.y = cvt_pk_bf16(oacc[db][qi][4 * g4 + 2] * inv, oacc[db][qi][4 * g4 + 3] * inv);
;                     *(u32x2*)(orow + 32 * db + 8 * g4 + 4 * hl) = w;
;                 }
;         }
;     }
.LBB0_455:
	s_lshl_b32 s6, s35, 1
	s_add_i32 s34, s34, s24
	v_mov_b32_e32 v68, v196
	v_mov_b32_e32 v66, v196
	v_mov_b32_e32 v220, v1
	s_nop 0
	v_permlane32_swap_b32_e32 v68, v66
	v_permlane32_swap_b32_e32 v1, v220
	v_add_f32_e32 v68, v68, v66
	v_add_f32_e32 v1, v1, v220
	v_div_scale_f32 v69, s[4:5], v68, v68, 1.0
	v_rcp_f32_e32 v71, v69
	v_div_scale_f32 v72, vcc, 1.0, v68, 1.0
	v_fma_f32 v73, -v69, v71, 1.0
	v_fmac_f32_e32 v71, v73, v71
	v_mul_f32_e32 v73, v72, v71
	v_fma_f32 v74, -v69, v73, v72
	v_fmac_f32_e32 v73, v74, v71
	v_fma_f32 v69, -v69, v73, v72
	v_div_fmas_f32 v69, v69, v71, v73
	v_div_fixup_f32 v71, v69, v68, 1.0
	v_div_scale_f32 v224, s[4:5], v1, v1, 1.0
	v_rcp_f32_e32 v225, v224
	v_div_scale_f32 v221, vcc, 1.0, v1, 1.0
	v_fma_f32 v223, -v224, v225, 1.0
	v_fmac_f32_e32 v225, v223, v225
	v_mul_f32_e32 v222, v221, v225
	v_fma_f32 v223, -v224, v222, v221
	v_fmac_f32_e32 v222, v223, v225
	v_fma_f32 v221, -v224, v222, v221
	v_div_fmas_f32 v221, v221, v225, v222
	v_div_fixup_f32 v1, v221, v1, 1.0
	s_lshl_b32 s20, s56, 7
	v_and_b32_e32 v232, 31, v195
	v_lshrrev_b32_e32 v233, 5, v195
	v_and_b32_e32 v234, 7, v232
	v_xor_b32_e32 v234, v234, v233
	v_lshlrev_b32_e32 v234, 4, v234
	v_lshl_add_u32 v234, v232, 7, v234
	v_add_u32_e32 v234, s20, v234
	v_xor_b32_e32 v235, 32, v234
	v_xor_b32_e32 v236, 64, v234
	v_xor_b32_e32 v237, 0x60, v234
	v_lshrrev_b32_e32 v238, 3, v195
	v_and_b32_e32 v239, 7, v195
	v_xor_b32_e32 v240, v239, v238
	v_lshlrev_b32_e32 v240, 4, v240
	v_lshl_add_u32 v240, v238, 7, v240
	v_add_u32_e32 v240, s20, v240
	v_and_b32_e32 v241, -32, v176
	v_or_b32_e32 v241, v241, v238
	v_lshlrev_b32_e32 v241, 10, v241
	v_lshl_add_u32 v241, v239, 4, v241
	v_add_u32_e32 v241, s6, v241
	v_readfirstlane_b32 s28, v168
	v_readfirstlane_b32 s29, v169
	s_sub_u32 s28, s28, 0x8000000
	s_subb_u32 s29, s29, 0
	v_mul_f32_e32 v34, v34, v71
	v_mul_f32_e32 v35, v35, v71
	v_mul_f32_e32 v36, v36, v71
	v_mul_f32_e32 v37, v37, v71
	v_mul_f32_e32 v38, v38, v71
	v_mul_f32_e32 v39, v39, v71
	v_mul_f32_e32 v40, v40, v71
	v_mul_f32_e32 v41, v41, v71
	v_cvt_pk_bf16_f32 v34, v34, v35
	v_cvt_pk_bf16_f32 v35, v36, v37
	v_cvt_pk_bf16_f32 v36, v38, v39
	v_cvt_pk_bf16_f32 v37, v40, v41
	s_nop 1
	v_permlane32_swap_b32_e32 v34, v36
	v_permlane32_swap_b32_e32 v35, v37
	ds_write_b128 v236, v[34:37]
	v_mul_f32_e32 v42, v42, v71
	v_mul_f32_e32 v43, v43, v71
	v_mul_f32_e32 v44, v44, v71
	v_mul_f32_e32 v45, v45, v71
	v_mul_f32_e32 v46, v46, v71
	v_mul_f32_e32 v47, v47, v71
	v_mul_f32_e32 v48, v48, v71
	v_mul_f32_e32 v49, v49, v71
	v_cvt_pk_bf16_f32 v42, v42, v43
	v_cvt_pk_bf16_f32 v43, v44, v45
	v_cvt_pk_bf16_f32 v44, v46, v47
	v_cvt_pk_bf16_f32 v45, v48, v49
	s_nop 1
	v_permlane32_swap_b32_e32 v42, v44
	v_permlane32_swap_b32_e32 v43, v45
	ds_write_b128 v237, v[42:45]
	v_mul_f32_e32 v50, v50, v71
	v_mul_f32_e32 v51, v51, v71
	v_mul_f32_e32 v52, v52, v71
	v_mul_f32_e32 v53, v53, v71
	v_mul_f32_e32 v54, v54, v71
	v_mul_f32_e32 v55, v55, v71
	v_mul_f32_e32 v56, v56, v71
	v_mul_f32_e32 v57, v57, v71
	v_cvt_pk_bf16_f32 v50, v50, v51
	v_cvt_pk_bf16_f32 v51, v52, v53
	v_cvt_pk_bf16_f32 v52, v54, v55
	v_cvt_pk_bf16_f32 v53, v56, v57
	s_nop 1
	v_permlane32_swap_b32_e32 v50, v52
	v_permlane32_swap_b32_e32 v51, v53
	ds_write_b128 v234, v[50:53]
	v_mul_f32_e32 v58, v58, v71
	v_mul_f32_e32 v59, v59, v71
	v_mul_f32_e32 v60, v60, v71
	v_mul_f32_e32 v61, v61, v71
	v_mul_f32_e32 v62, v62, v71
	v_mul_f32_e32 v63, v63, v71
	v_mul_f32_e32 v64, v64, v71
	v_mul_f32_e32 v65, v65, v71
	v_cvt_pk_bf16_f32 v58, v58, v59
	v_cvt_pk_bf16_f32 v59, v60, v61
	v_cvt_pk_bf16_f32 v60, v62, v63
	v_cvt_pk_bf16_f32 v61, v64, v65
	s_nop 1
	v_permlane32_swap_b32_e32 v58, v60
	v_permlane32_swap_b32_e32 v59, v61
	ds_write_b128 v235, v[58:61]
	v_mul_f32_e32 v18, v18, v1
	v_mul_f32_e32 v19, v19, v1
	v_mul_f32_e32 v20, v20, v1
	v_mul_f32_e32 v21, v21, v1
	v_mul_f32_e32 v22, v22, v1
	v_mul_f32_e32 v23, v23, v1
	v_mul_f32_e32 v24, v24, v1
	v_mul_f32_e32 v25, v25, v1
	v_cvt_pk_bf16_f32 v18, v18, v19
	v_cvt_pk_bf16_f32 v19, v20, v21
	v_cvt_pk_bf16_f32 v20, v22, v23
	v_cvt_pk_bf16_f32 v21, v24, v25
	s_nop 1
	v_permlane32_swap_b32_e32 v18, v20
	v_permlane32_swap_b32_e32 v19, v21
	ds_write_b128 v234, v[18:21] offset:4096
	v_mul_f32_e32 v26, v26, v1
	v_mul_f32_e32 v27, v27, v1
	v_mul_f32_e32 v28, v28, v1
	v_mul_f32_e32 v29, v29, v1
	v_mul_f32_e32 v30, v30, v1
	v_mul_f32_e32 v31, v31, v1
	v_mul_f32_e32 v32, v32, v1
	v_mul_f32_e32 v33, v33, v1
	v_cvt_pk_bf16_f32 v26, v26, v27
	v_cvt_pk_bf16_f32 v27, v28, v29
	v_cvt_pk_bf16_f32 v28, v30, v31
	v_cvt_pk_bf16_f32 v29, v32, v33
	s_nop 1
	v_permlane32_swap_b32_e32 v26, v28
	v_permlane32_swap_b32_e32 v27, v29
	ds_write_b128 v235, v[26:29] offset:4096
	v_mul_f32_e32 v2, v2, v1
	v_mul_f32_e32 v3, v3, v1
	v_mul_f32_e32 v4, v4, v1
	v_mul_f32_e32 v5, v5, v1
	v_mul_f32_e32 v6, v6, v1
	v_mul_f32_e32 v7, v7, v1
	v_mul_f32_e32 v8, v8, v1
	v_mul_f32_e32 v9, v9, v1
	v_cvt_pk_bf16_f32 v2, v2, v3
	v_cvt_pk_bf16_f32 v3, v4, v5
	v_cvt_pk_bf16_f32 v4, v6, v7
	v_cvt_pk_bf16_f32 v5, v8, v9
	s_nop 1
	v_permlane32_swap_b32_e32 v2, v4
	v_permlane32_swap_b32_e32 v3, v5
	ds_write_b128 v236, v[2:5] offset:4096
	v_mul_f32_e32 v10, v10, v1
	v_mul_f32_e32 v11, v11, v1
	v_mul_f32_e32 v12, v12, v1
	v_mul_f32_e32 v13, v13, v1
	v_mul_f32_e32 v14, v14, v1
	v_mul_f32_e32 v15, v15, v1
	v_mul_f32_e32 v16, v16, v1
	v_mul_f32_e32 v17, v17, v1
	v_cvt_pk_bf16_f32 v10, v10, v11
	v_cvt_pk_bf16_f32 v11, v12, v13
	v_cvt_pk_bf16_f32 v12, v14, v15
	v_cvt_pk_bf16_f32 v13, v16, v17
	s_nop 1
	v_permlane32_swap_b32_e32 v10, v12
	v_permlane32_swap_b32_e32 v11, v13
	ds_write_b128 v237, v[10:13] offset:4096
	ds_read_b128 v[66:69], v240
	ds_read_b128 v[70:73], v240 offset:1024
	ds_read_b128 v[74:77], v240 offset:2048
	ds_read_b128 v[78:81], v240 offset:3072
	ds_read_b128 v[130:133], v240 offset:4096
	ds_read_b128 v[134:137], v240 offset:5120
	ds_read_b128 v[138:141], v240 offset:6144
	ds_read_b128 v[142:145], v240 offset:7168
	v_add_u32_e32 v242, 0x2000, v241
	v_add_u32_e32 v243, 0x4000, v241
	v_add_u32_e32 v244, 0x6000, v241
	v_add_u32_e32 v245, 0x8000, v241
	v_add_u32_e32 v246, 0xa000, v241
	v_add_u32_e32 v247, 0xc000, v241
	v_add_u32_e32 v248, 0xe000, v241
	s_waitcnt lgkmcnt(7)
	global_store_dwordx4 v241, v[66:69], s[28:29]
	s_waitcnt lgkmcnt(6)
	global_store_dwordx4 v242, v[70:73], s[28:29]
	s_waitcnt lgkmcnt(5)
	global_store_dwordx4 v243, v[74:77], s[28:29]
	s_waitcnt lgkmcnt(4)
	global_store_dwordx4 v244, v[78:81], s[28:29]
	s_waitcnt lgkmcnt(3)
	global_store_dwordx4 v245, v[130:133], s[28:29]
	s_waitcnt lgkmcnt(2)
	global_store_dwordx4 v246, v[134:137], s[28:29]
	s_waitcnt lgkmcnt(1)
	global_store_dwordx4 v247, v[138:141], s[28:29]
	s_waitcnt lgkmcnt(0)
	global_store_dwordx4 v248, v[142:145], s[28:29]
	s_cmpk_gt_i32 s34, 0x1ff
	s_cbranch_scc1 .LBB0_489
